# independent cache conversions moved into GEMM tail idle time: MLA caches (ckv, kr) from phase 9 into phase-8 tail workgroups, band K cache from phase 0 into phase-1 tail workgroups
# baseline (speedup 1.0000x reference)
; DI unsigned cvtpk(float lo, float hi) { unsigned r; asm volatile("v_cvt_pk_bf16_f32 %0, %1, %2" : "=v"(r) : "v"(lo), "v"(hi)); return r; }
; #define CVT_C_ST(va, vb) *(u32x4*)((bf16*)(ws + A_CKVS) + (g##va / (2048 * 64)) * 2112 * 512 + (g##va % (2048 * 64)) * 8) = pack8(va, vb)
; __global__ void __launch_bounds__(512) fwd_mega(Args a_) {
;     ...
;       { const size_t ng = (size_t)16 * 2048 * 64;
;     ...
;         size_t i = gt;
;         for (; i + 3 * NGT < ng; i += 4 * NGT) { CVT_C_LD(i, p0, p1); CVT_C_LD(i + NGT, q0, q1); CVT_C_LD(i + 2 * NGT, r0, r1); CVT_C_LD(i + 3 * NGT, t0, t1);
;           CVT_C_ST(p0, p1); CVT_C_ST(q0, q1); CVT_C_ST(r0, r1); CVT_C_ST(t0, t1); }
;         for (; i < ng; i += NGT) { CVT_C_LD(i, p0, p1); CVT_C_ST(p0, p1); }
;     ...
;       }
;       { const size_t ng = (size_t)16 * 2048 * 8;
;         for (size_t i = gt; i < ng; i += NGT) { const size_t rowi = i >> 3; const int q = (int)(i & 7); const size_t b = rowi / 2048, r = rowi % 2048;
;           const float* src = a.in[5] + rowi * 64 + 4 * q; const f32x4 x1 = *(const f32x4*)src, x2 = *(const f32x4*)(src + 32);
;           u32x4 w; w.x = cvtpk(x1.x, x2.x); w.y = cvtpk(x1.y, x2.y); w.z = cvtpk(x1.z, x2.z); w.w = cvtpk(x1.w, x2.w);
;           *(u32x4*)((bf16*)(ws + A_KRS) + (b * 2112 + r) * 64 + 8 * q) = w; } }
.LBB0_180:
	s_and_b64 vcc, exec, s[78:79]
	s_cbranch_vccz .Ltc_p9orig
	s_mov_b32 s20, s22
	s_mov_b64 s[22:23], s[34:35]
	s_mov_b64 s[6:7], 0
	s_branch .LBB0_191

; #define CVT_A_ST(va, vb) *(u32x4*)((bf16*)(ws + (isv##va ? A_VS : A_KS)) + (g##va / (512 * 256)) * 576 * 2048 + (g##va % (512 * 256)) * 8) = pack8(va, vb)
; __global__ void __launch_bounds__(512) fwd_mega(Args a_) {
;     ...
;         { const size_t ng = (size_t)16 * 512 * 256;
;     ...
;           size_t i = gt;
;           for (; i + 3 * NGT < 2 * ng; i += 4 * NGT) { CVT_A_LD(i, p0, p1); CVT_A_LD(i + NGT, q0, q1); CVT_A_LD(i + 2 * NGT, r0, r1); CVT_A_LD(i + 3 * NGT, t0, t1);
;             CVT_A_ST(p0, p1); CVT_A_ST(q0, q1); CVT_A_ST(r0, r1); CVT_A_ST(t0, t1); }
;           for (; i < 2 * ng; i += NGT) { CVT_A_LD(i, p0, p1); CVT_A_ST(p0, p1); }
.Lp0_entry:
	s_lshl_b32 s0, s81, 6
	v_add_u32_e32 v160, s0, v184
	v_lshlrev_b32_e32 v161, 4, v160
	v_lshlrev_b32_e32 v160, 5, v160
	s_load_dwordx4 s[4:7], s[22:23], 0x10
	s_add_u32 s2, s54, 0x1e400000
	s_addc_u32 s3, s55, 0
	s_waitcnt lgkmcnt(0)
	s_mov_b64 s[0:1], s[6:7]
	s_mov_b32 s8, 2

; #define CVT_A_ST(va, vb) *(u32x4*)((bf16*)(ws + (isv##va ? A_VS : A_KS)) + (g##va / (512 * 256)) * 576 * 2048 + (g##va % (512 * 256)) * 8) = pack8(va, vb)
; #define CVT_C_ST(va, vb) *(u32x4*)((bf16*)(ws + A_CKVS) + (g##va / (2048 * 64)) * 2112 * 512 + (g##va % (2048 * 64)) * 8) = pack8(va, vb)
; __global__ void __launch_bounds__(512) fwd_mega(Args a_) {
;     ...
;         { const size_t ng = (size_t)16 * 512 * 256;
;     ...
;           size_t i = gt;
;           for (; i + 3 * NGT < 2 * ng; i += 4 * NGT) { CVT_A_LD(i, p0, p1); CVT_A_LD(i + NGT, q0, q1); CVT_A_LD(i + 2 * NGT, r0, r1); CVT_A_LD(i + 3 * NGT, t0, t1);
;             CVT_A_ST(p0, p1); CVT_A_ST(q0, q1); CVT_A_ST(r0, r1); CVT_A_ST(t0, t1); }
;           for (; i < 2 * ng; i += NGT) { CVT_A_LD(i, p0, p1); CVT_A_ST(p0, p1); }
;     ...
;       { const size_t ng = (size_t)16 * 2048 * 64;
;     ...
;         size_t i = gt;
;         for (; i + 3 * NGT < ng; i += 4 * NGT) { CVT_C_LD(i, p0, p1); CVT_C_LD(i + NGT, q0, q1); CVT_C_LD(i + 2 * NGT, r0, r1); CVT_C_LD(i + 3 * NGT, t0, t1);
;           CVT_C_ST(p0, p1); CVT_C_ST(q0, q1); CVT_C_ST(r0, r1); CVT_C_ST(t0, t1); }
;         for (; i < ng; i += NGT) { CVT_C_LD(i, p0, p1); CVT_C_ST(p0, p1); }
.Ltk_entry:
	v_readlane_b32 s3, v255, 36
	s_add_i32 s2, s81, s3
	s_sub_i32 s2, s2, 0x300
	s_cmp_lt_i32 s2, 0
	s_cbranch_scc1 .Ltk_skip
	s_cmpk_lt_i32 s2, 0x400
	s_cbranch_scc0 .Ltk_skip
	s_load_dwordx2 s[4:5], s[28:29], 0x10
	s_lshl_b32 s2, s2, 6
	v_add_u32_e32 v96, s2, v186
	v_lshlrev_b32_e32 v97, 4, v96
	v_lshlrev_b32_e32 v96, 5, v96
	s_add_u32 s6, s54, 0x1c000000
	s_addc_u32 s7, s55, 0
	s_mov_b32 s8, 0
	s_waitcnt lgkmcnt(0)
.Ltk_loop:
	global_load_dwordx4 v[0:3], v96, s[4:5]
	global_load_dwordx4 v[4:7], v96, s[4:5] offset:16
	s_add_u32 s4, s4, 0x200000
	s_addc_u32 s5, s5, 0
	global_load_dwordx4 v[8:11], v96, s[4:5]
	global_load_dwordx4 v[12:15], v96, s[4:5] offset:16
	s_add_u32 s4, s4, 0x200000
	s_addc_u32 s5, s5, 0
	global_load_dwordx4 v[16:19], v96, s[4:5]
	global_load_dwordx4 v[20:23], v96, s[4:5] offset:16
	s_add_u32 s4, s4, 0x200000
	s_addc_u32 s5, s5, 0
	global_load_dwordx4 v[24:27], v96, s[4:5]
	global_load_dwordx4 v[28:31], v96, s[4:5] offset:16
	s_add_u32 s4, s4, 0x200000
	s_addc_u32 s5, s5, 0
	global_load_dwordx4 v[32:35], v96, s[4:5]
	global_load_dwordx4 v[36:39], v96, s[4:5] offset:16
	s_add_u32 s4, s4, 0x200000
	s_addc_u32 s5, s5, 0
	global_load_dwordx4 v[40:43], v96, s[4:5]
	global_load_dwordx4 v[44:47], v96, s[4:5] offset:16
	s_add_u32 s4, s4, 0x200000
	s_addc_u32 s5, s5, 0
	global_load_dwordx4 v[48:51], v96, s[4:5]
	global_load_dwordx4 v[52:55], v96, s[4:5] offset:16
	s_add_u32 s4, s4, 0x200000
	s_addc_u32 s5, s5, 0
	global_load_dwordx4 v[56:59], v96, s[4:5]
	global_load_dwordx4 v[60:63], v96, s[4:5] offset:16
	s_add_u32 s4, s4, 0x200000
	s_addc_u32 s5, s5, 0
	s_waitcnt vmcnt(14)
	v_cvt_pk_bf16_f32 v0, v0, v1
	v_cvt_pk_bf16_f32 v1, v2, v3
	v_cvt_pk_bf16_f32 v2, v4, v5
	v_cvt_pk_bf16_f32 v3, v6, v7
	global_store_dwordx4 v97, v[0:3], s[6:7]
	s_add_u32 s6, s6, 0x100000
	s_addc_u32 s7, s7, 0
	s_waitcnt vmcnt(13)
	v_cvt_pk_bf16_f32 v8, v8, v9
	v_cvt_pk_bf16_f32 v9, v10, v11
	v_cvt_pk_bf16_f32 v10, v12, v13
	v_cvt_pk_bf16_f32 v11, v14, v15
	global_store_dwordx4 v97, v[8:11], s[6:7]
	s_add_u32 s6, s6, 0x140000
	s_addc_u32 s7, s7, 0
	s_waitcnt vmcnt(12)
	v_cvt_pk_bf16_f32 v16, v16, v17
	v_cvt_pk_bf16_f32 v17, v18, v19
	v_cvt_pk_bf16_f32 v18, v20, v21
	v_cvt_pk_bf16_f32 v19, v22, v23
	global_store_dwordx4 v97, v[16:19], s[6:7]
	s_add_u32 s6, s6, 0x100000
	s_addc_u32 s7, s7, 0
	s_waitcnt vmcnt(11)
	v_cvt_pk_bf16_f32 v24, v24, v25
	v_cvt_pk_bf16_f32 v25, v26, v27
	v_cvt_pk_bf16_f32 v26, v28, v29
	v_cvt_pk_bf16_f32 v27, v30, v31
	global_store_dwordx4 v97, v[24:27], s[6:7]
	s_add_u32 s6, s6, 0x140000
	s_addc_u32 s7, s7, 0
	s_waitcnt vmcnt(10)
	v_cvt_pk_bf16_f32 v32, v32, v33
	v_cvt_pk_bf16_f32 v33, v34, v35
	v_cvt_pk_bf16_f32 v34, v36, v37
	v_cvt_pk_bf16_f32 v35, v38, v39
	global_store_dwordx4 v97, v[32:35], s[6:7]
	s_add_u32 s6, s6, 0x100000
	s_addc_u32 s7, s7, 0
	s_waitcnt vmcnt(9)
	v_cvt_pk_bf16_f32 v40, v40, v41
	v_cvt_pk_bf16_f32 v41, v42, v43
	v_cvt_pk_bf16_f32 v42, v44, v45
	v_cvt_pk_bf16_f32 v43, v46, v47
	global_store_dwordx4 v97, v[40:43], s[6:7]
	s_add_u32 s6, s6, 0x140000
	s_addc_u32 s7, s7, 0
	s_waitcnt vmcnt(8)
	v_cvt_pk_bf16_f32 v48, v48, v49
	v_cvt_pk_bf16_f32 v49, v50, v51
	v_cvt_pk_bf16_f32 v50, v52, v53
	v_cvt_pk_bf16_f32 v51, v54, v55
	global_store_dwordx4 v97, v[48:51], s[6:7]
	s_add_u32 s6, s6, 0x100000
	s_addc_u32 s7, s7, 0
	s_waitcnt vmcnt(7)
	v_cvt_pk_bf16_f32 v56, v56, v57
	v_cvt_pk_bf16_f32 v57, v58, v59
	v_cvt_pk_bf16_f32 v58, v60, v61
	v_cvt_pk_bf16_f32 v59, v62, v63
	global_store_dwordx4 v97, v[56:59], s[6:7]
	s_add_u32 s6, s6, 0x140000
	s_addc_u32 s7, s7, 0
	s_add_i32 s8, s8, 1
	s_cmp_lt_u32 s8, 4
	s_cbranch_scc1 .Ltk_loop
	s_branch .Ltk_skip
.Ltc_entry:
	s_cmpk_lt_u32 s1, 0x500
	s_cbranch_scc1 .Ltc_done
	s_cmpk_lt_u32 s0, 0x400
	s_cbranch_scc0 .Ltc_kr
	s_load_dwordx2 s[2:3], s[28:29], 0x20
	s_lshl_b32 s4, s0, 6
	v_add_u32_e32 v96, s4, v186
	v_lshlrev_b32_e32 v97, 4, v96
	v_lshlrev_b32_e32 v96, 5, v96
	s_add_u32 s4, s54, 0x10c00000
	s_addc_u32 s5, s55, 0
	s_mov_b32 s6, 0
	s_waitcnt lgkmcnt(0)
; DI unsigned cvtpk(float lo, float hi) { unsigned r; asm volatile("v_cvt_pk_bf16_f32 %0, %1, %2" : "=v"(r) : "v"(lo), "v"(hi)); return r; }
; #define CVT_C_ST(va, vb) *(u32x4*)((bf16*)(ws + A_CKVS) + (g##va / (2048 * 64)) * 2112 * 512 + (g##va % (2048 * 64)) * 8) = pack8(va, vb)
; __global__ void __launch_bounds__(512) fwd_mega(Args a_) {
;     ...
;       { const size_t ng = (size_t)16 * 2048 * 64;
;     ...
;         size_t i = gt;
;         for (; i + 3 * NGT < ng; i += 4 * NGT) { CVT_C_LD(i, p0, p1); CVT_C_LD(i + NGT, q0, q1); CVT_C_LD(i + 2 * NGT, r0, r1); CVT_C_LD(i + 3 * NGT, t0, t1);
;           CVT_C_ST(p0, p1); CVT_C_ST(q0, q1); CVT_C_ST(r0, r1); CVT_C_ST(t0, t1); }
;         for (; i < ng; i += NGT) { CVT_C_LD(i, p0, p1); CVT_C_ST(p0, p1); }
;     ...
;       { const size_t ng = (size_t)16 * 2048 * 8;
;         for (size_t i = gt; i < ng; i += NGT) { const size_t rowi = i >> 3; const int q = (int)(i & 7); const size_t b = rowi / 2048, r = rowi % 2048;
;           const float* src = a.in[5] + rowi * 64 + 4 * q; const f32x4 x1 = *(const f32x4*)src, x2 = *(const f32x4*)(src + 32);
;           u32x4 w; w.x = cvtpk(x1.x, x2.x); w.y = cvtpk(x1.y, x2.y); w.z = cvtpk(x1.z, x2.z); w.w = cvtpk(x1.w, x2.w);
;           *(u32x4*)((bf16*)(ws + A_KRS) + (b * 2112 + r) * 64 + 8 * q) = w; } }
.Ltc_ckv_loop:
	global_load_dwordx4 v[0:3], v96, s[2:3]
	global_load_dwordx4 v[4:7], v96, s[2:3] offset:16
	s_add_u32 s2, s2, 0x200000
	s_addc_u32 s3, s3, 0
	global_load_dwordx4 v[8:11], v96, s[2:3]
	global_load_dwordx4 v[12:15], v96, s[2:3] offset:16
	s_add_u32 s2, s2, 0x200000
	s_addc_u32 s3, s3, 0
	global_load_dwordx4 v[16:19], v96, s[2:3]
	global_load_dwordx4 v[20:23], v96, s[2:3] offset:16
	s_add_u32 s2, s2, 0x200000
	s_addc_u32 s3, s3, 0
	global_load_dwordx4 v[24:27], v96, s[2:3]
	global_load_dwordx4 v[28:31], v96, s[2:3] offset:16
	s_add_u32 s2, s2, 0x200000
	s_addc_u32 s3, s3, 0
	global_load_dwordx4 v[32:35], v96, s[2:3]
	global_load_dwordx4 v[36:39], v96, s[2:3] offset:16
	s_add_u32 s2, s2, 0x200000
	s_addc_u32 s3, s3, 0
	global_load_dwordx4 v[40:43], v96, s[2:3]
	global_load_dwordx4 v[44:47], v96, s[2:3] offset:16
	s_add_u32 s2, s2, 0x200000
	s_addc_u32 s3, s3, 0
	global_load_dwordx4 v[48:51], v96, s[2:3]
	global_load_dwordx4 v[52:55], v96, s[2:3] offset:16
	s_add_u32 s2, s2, 0x200000
	s_addc_u32 s3, s3, 0
	global_load_dwordx4 v[56:59], v96, s[2:3]
	global_load_dwordx4 v[60:63], v96, s[2:3] offset:16
	s_add_u32 s2, s2, 0x200000
	s_addc_u32 s3, s3, 0
	s_waitcnt vmcnt(14)
	v_cvt_pk_bf16_f32 v0, v0, v1
	v_cvt_pk_bf16_f32 v1, v2, v3
	v_cvt_pk_bf16_f32 v2, v4, v5
	v_cvt_pk_bf16_f32 v3, v6, v7
	global_store_dwordx4 v97, v[0:3], s[4:5]
	s_add_u32 s4, s4, 0x100000
	s_addc_u32 s5, s5, 0
	s_waitcnt vmcnt(13)
	v_cvt_pk_bf16_f32 v8, v8, v9
	v_cvt_pk_bf16_f32 v9, v10, v11
	v_cvt_pk_bf16_f32 v10, v12, v13
	v_cvt_pk_bf16_f32 v11, v14, v15
	global_store_dwordx4 v97, v[8:11], s[4:5]
	s_add_u32 s4, s4, 0x110000
	s_addc_u32 s5, s5, 0
	s_waitcnt vmcnt(12)
	v_cvt_pk_bf16_f32 v16, v16, v17
	v_cvt_pk_bf16_f32 v17, v18, v19
	v_cvt_pk_bf16_f32 v18, v20, v21
	v_cvt_pk_bf16_f32 v19, v22, v23
	global_store_dwordx4 v97, v[16:19], s[4:5]
	s_add_u32 s4, s4, 0x100000
	s_addc_u32 s5, s5, 0
	s_waitcnt vmcnt(11)
	v_cvt_pk_bf16_f32 v24, v24, v25
	v_cvt_pk_bf16_f32 v25, v26, v27
	v_cvt_pk_bf16_f32 v26, v28, v29
	v_cvt_pk_bf16_f32 v27, v30, v31
	global_store_dwordx4 v97, v[24:27], s[4:5]
	s_add_u32 s4, s4, 0x110000
	s_addc_u32 s5, s5, 0
	s_waitcnt vmcnt(10)
	v_cvt_pk_bf16_f32 v32, v32, v33
	v_cvt_pk_bf16_f32 v33, v34, v35
	v_cvt_pk_bf16_f32 v34, v36, v37
	v_cvt_pk_bf16_f32 v35, v38, v39
	global_store_dwordx4 v97, v[32:35], s[4:5]
	s_add_u32 s4, s4, 0x100000
	s_addc_u32 s5, s5, 0
	s_waitcnt vmcnt(9)
	v_cvt_pk_bf16_f32 v40, v40, v41
	v_cvt_pk_bf16_f32 v41, v42, v43
	v_cvt_pk_bf16_f32 v42, v44, v45
	v_cvt_pk_bf16_f32 v43, v46, v47
	global_store_dwordx4 v97, v[40:43], s[4:5]
	s_add_u32 s4, s4, 0x110000
	s_addc_u32 s5, s5, 0
	s_waitcnt vmcnt(8)
	v_cvt_pk_bf16_f32 v48, v48, v49
	v_cvt_pk_bf16_f32 v49, v50, v51
	v_cvt_pk_bf16_f32 v50, v52, v53
	v_cvt_pk_bf16_f32 v51, v54, v55
	global_store_dwordx4 v97, v[48:51], s[4:5]
	s_add_u32 s4, s4, 0x100000
	s_addc_u32 s5, s5, 0
	s_waitcnt vmcnt(7)
	v_cvt_pk_bf16_f32 v56, v56, v57
	v_cvt_pk_bf16_f32 v57, v58, v59
	v_cvt_pk_bf16_f32 v58, v60, v61
	v_cvt_pk_bf16_f32 v59, v62, v63
	global_store_dwordx4 v97, v[56:59], s[4:5]
	s_add_u32 s4, s4, 0x110000
	s_addc_u32 s5, s5, 0
	s_add_i32 s6, s6, 1
	s_cmp_lt_u32 s6, 4
	s_cbranch_scc1 .Ltc_ckv_loop
	s_branch .Ltc_done
.Ltc_kr:
	s_cmpk_lt_u32 s0, 0x500
	s_cbranch_scc0 .Ltc_done
	s_load_dwordx2 s[2:3], s[28:29], 0x28
	s_sub_i32 s4, s0, 0x400
	s_lshl_b32 s4, s4, 6
	v_add_u32_e32 v96, s4, v186
	v_lshrrev_b32_e32 v98, 3, v96
	v_and_b32_e32 v99, 7, v96
	v_lshlrev_b32_e32 v99, 4, v99
	v_lshl_add_u32 v96, v98, 8, v99
	v_lshl_add_u32 v97, v98, 7, v99
	s_add_u32 s4, s54, 0x12f00000
	s_addc_u32 s5, s55, 0
	s_mov_b32 s6, 0
	s_waitcnt lgkmcnt(0)
.Ltc_kr_loop:
	global_load_dwordx4 v[0:3], v96, s[2:3]
	global_load_dwordx4 v[4:7], v96, s[2:3] offset:128
	s_add_u32 s2, s2, 0x80000
	s_addc_u32 s3, s3, 0
	global_load_dwordx4 v[8:11], v96, s[2:3]
	global_load_dwordx4 v[12:15], v96, s[2:3] offset:128
	s_add_u32 s2, s2, 0x80000
	s_addc_u32 s3, s3, 0
	global_load_dwordx4 v[16:19], v96, s[2:3]
	global_load_dwordx4 v[20:23], v96, s[2:3] offset:128
	s_add_u32 s2, s2, 0x80000
	s_addc_u32 s3, s3, 0
	global_load_dwordx4 v[24:27], v96, s[2:3]
	global_load_dwordx4 v[28:31], v96, s[2:3] offset:128
	s_add_u32 s2, s2, 0x80000
	s_addc_u32 s3, s3, 0
	global_load_dwordx4 v[32:35], v96, s[2:3]
	global_load_dwordx4 v[36:39], v96, s[2:3] offset:128
	s_add_u32 s2, s2, 0x80000
	s_addc_u32 s3, s3, 0
	global_load_dwordx4 v[40:43], v96, s[2:3]
	global_load_dwordx4 v[44:47], v96, s[2:3] offset:128
	s_add_u32 s2, s2, 0x80000
	s_addc_u32 s3, s3, 0
	global_load_dwordx4 v[48:51], v96, s[2:3]
	global_load_dwordx4 v[52:55], v96, s[2:3] offset:128
	s_add_u32 s2, s2, 0x80000
	s_addc_u32 s3, s3, 0
	global_load_dwordx4 v[56:59], v96, s[2:3]
	global_load_dwordx4 v[60:63], v96, s[2:3] offset:128
	s_add_u32 s2, s2, 0x80000
	s_addc_u32 s3, s3, 0
	s_waitcnt vmcnt(14)
	v_cvt_pk_bf16_f32 v0, v0, v4
	v_cvt_pk_bf16_f32 v1, v1, v5
	v_cvt_pk_bf16_f32 v2, v2, v6
	v_cvt_pk_bf16_f32 v3, v3, v7
	global_store_dwordx4 v97, v[0:3], s[4:5]
	s_add_u32 s4, s4, 0x42000
	s_addc_u32 s5, s5, 0
	s_waitcnt vmcnt(13)
	v_cvt_pk_bf16_f32 v8, v8, v12
	v_cvt_pk_bf16_f32 v9, v9, v13
	v_cvt_pk_bf16_f32 v10, v10, v14
	v_cvt_pk_bf16_f32 v11, v11, v15
	global_store_dwordx4 v97, v[8:11], s[4:5]
	s_add_u32 s4, s4, 0x42000
	s_addc_u32 s5, s5, 0
	s_waitcnt vmcnt(12)
	v_cvt_pk_bf16_f32 v16, v16, v20
	v_cvt_pk_bf16_f32 v17, v17, v21
	v_cvt_pk_bf16_f32 v18, v18, v22
	v_cvt_pk_bf16_f32 v19, v19, v23
	global_store_dwordx4 v97, v[16:19], s[4:5]
	s_add_u32 s4, s4, 0x42000
	s_addc_u32 s5, s5, 0
	s_waitcnt vmcnt(11)
	v_cvt_pk_bf16_f32 v24, v24, v28
	v_cvt_pk_bf16_f32 v25, v25, v29
	v_cvt_pk_bf16_f32 v26, v26, v30
	v_cvt_pk_bf16_f32 v27, v27, v31
	global_store_dwordx4 v97, v[24:27], s[4:5]
	s_add_u32 s4, s4, 0x42000
	s_addc_u32 s5, s5, 0
	s_waitcnt vmcnt(10)
	v_cvt_pk_bf16_f32 v32, v32, v36
	v_cvt_pk_bf16_f32 v33, v33, v37
	v_cvt_pk_bf16_f32 v34, v34, v38
	v_cvt_pk_bf16_f32 v35, v35, v39
	global_store_dwordx4 v97, v[32:35], s[4:5]
	s_add_u32 s4, s4, 0x42000
	s_addc_u32 s5, s5, 0
	s_waitcnt vmcnt(9)
	v_cvt_pk_bf16_f32 v40, v40, v44
	v_cvt_pk_bf16_f32 v41, v41, v45
	v_cvt_pk_bf16_f32 v42, v42, v46
	v_cvt_pk_bf16_f32 v43, v43, v47
	global_store_dwordx4 v97, v[40:43], s[4:5]
	s_add_u32 s4, s4, 0x42000
	s_addc_u32 s5, s5, 0
	s_waitcnt vmcnt(8)
	v_cvt_pk_bf16_f32 v48, v48, v52
	v_cvt_pk_bf16_f32 v49, v49, v53
	v_cvt_pk_bf16_f32 v50, v50, v54
	v_cvt_pk_bf16_f32 v51, v51, v55
	global_store_dwordx4 v97, v[48:51], s[4:5]
	s_add_u32 s4, s4, 0x42000
	s_addc_u32 s5, s5, 0
	s_waitcnt vmcnt(7)
	v_cvt_pk_bf16_f32 v56, v56, v60
	v_cvt_pk_bf16_f32 v57, v57, v61
	v_cvt_pk_bf16_f32 v58, v58, v62
	v_cvt_pk_bf16_f32 v59, v59, v63
	global_store_dwordx4 v97, v[56:59], s[4:5]
	s_add_u32 s4, s4, 0x42000
	s_addc_u32 s5, s5, 0
	s_add_i32 s6, s6, 1
	s_cmp_lt_u32 s6, 2
	s_cbranch_scc1 .Ltc_kr_loop
.Ltc_done:
	s_mov_b64 s[8:9], 0
	s_branch .LBB0_861

; __global__ void __launch_bounds__(512) fwd_mega(Args a_) {
;     ...
;       if (ph == 1 || ph == 5 || ph == 8 || ph == 17) {
;         const int nwg_ = (gM / 256) * (gN / 256), rem_ = nwg_ % G;
;         int li_ = (int)blockIdx.x, nl_ = G;
;         if (rem_ != 0) { li_ = (int)blockIdx.x - rem_; nl_ = li_ >= 0 ? G - rem_ : 0; }
;         if (nl_ > 0) {
.LBB0_860:
	s_and_b64 vcc, exec, s[78:79]
	s_cbranch_vccnz .Ltc_entry
	s_mov_b64 s[8:9], 0

; #define LAS __attribute__((address_space(3)))
; __global__ void __launch_bounds__(512) fwd_mega(Args a_) {
;     ...
;       if (ph == 1 || ph == 5 || ph == 8 || ph == 17) {
;         const int nwg_ = (gM / 256) * (gN / 256), rem_ = nwg_ % G;
;         int li_ = (int)blockIdx.x, nl_ = G;
;         if (rem_ != 0) { li_ = (int)blockIdx.x - rem_; nl_ = li_ >= 0 ? G - rem_ : 0; }
;         if (nl_ > 0) {
;           LAS float* scr = (LAS float*)(lds + wave * 16640);
;           const int w0 = li_ * 8 + wave, nw = nl_ * 8;
;           if (ph == 1) {
.LBB0_943:
	v_readlane_b32 s3, v255, 35
	s_cmp_eq_u32 s3, 1
	s_cbranch_scc0 .Ltk_skip
	s_and_b64 vcc, exec, s[78:79]
	s_cbranch_vccnz .Ltk_entry
